# variant: non-temporal hint on the MLP-up output stores (write-once 268 MB intermediate)
# baseline (speedup 1.0000x reference)
.LBB0_1792:
	s_or_b64 exec, exec, s[70:71]
	ds_bpermute_b32 v146, v153, v159
	v_lshlrev_b64 v[160:161], 14, v[148:149]
	v_lshl_add_u64 v[160:161], s[50:51], 0, v[160:161]
	s_waitcnt lgkmcnt(0)
	v_add_f32_e32 v147, v159, v146
	ds_bpermute_b32 v159, v154, v147
	v_lshl_add_u32 v146, s68, 8, v152
	s_waitcnt lgkmcnt(0)
	v_add_f32_e32 v147, v147, v159
	v_fmamk_f32 v147, v147, 0x3a000000, v158
	v_rsq_f32_e32 v162, v147
	v_ashrrev_i32_e32 v147, 31, v146
	v_lshl_add_u64 v[160:161], v[146:147], 1, v[160:161]
	v_pk_mul_f32 v[120:121], v[120:121], v[162:163] op_sel_hi:[1,0]
	v_pk_mul_f32 v[124:125], v[124:125], v[162:163] op_sel_hi:[1,0]
	v_max_f32_e32 v120, 0, v120
	v_pk_mul_f32 v[126:127], v[126:127], v[162:163] op_sel_hi:[1,0]
	v_pk_mul_f32 v[122:123], v[122:123], v[162:163] op_sel_hi:[1,0]
	v_max_f32_e32 v125, 0, v125
	v_mul_f32_e32 v149, v120, v120
	v_max_f32_e32 v120, 0, v121
	v_mul_f32_e32 v121, v125, v125
	v_mul_f32_e32 v125, v120, v120
	v_max_f32_e32 v120, 0, v126
	v_max_f32_e32 v122, 0, v122
	v_max_f32_e32 v124, 0, v124
	v_mul_f32_e32 v126, v120, v120
	v_mul_f32_e32 v159, v122, v122
	v_max_f32_e32 v120, 0, v127
	v_max_f32_e32 v122, 0, v123
	v_mul_f32_e32 v124, v124, v124
	v_mul_f32_e32 v123, v120, v120
	v_mul_f32_e32 v127, v122, v122
	v_pk_mul_f32 v[114:115], v[114:115], v[162:163] op_sel_hi:[1,0]
	v_pk_mul_f32 v[112:113], v[112:113], v[162:163] op_sel_hi:[1,0]
	v_cvt_pk_bf16_f32 v120, v124, v121
	v_cvt_pk_bf16_f32 v121, v126, v123
	v_cvt_pk_bf16_f32 v122, v149, v125
	v_cvt_pk_bf16_f32 v123, v159, v127
	v_pk_mul_f32 v[118:119], v[118:119], v[162:163] op_sel_hi:[1,0]
	v_pk_mul_f32 v[116:117], v[116:117], v[162:163] op_sel_hi:[1,0]
	v_max_f32_e32 v112, 0, v112
	v_max_f32_e32 v113, 0, v113
	v_max_f32_e32 v114, 0, v114
	global_store_dwordx4 v[160:161], v[120:123], off nt
	v_max_f32_e32 v116, 0, v116
	v_max_f32_e32 v115, 0, v115
	v_mul_f32_e32 v120, v112, v112
	v_max_f32_e32 v112, 0, v117
	v_mul_f32_e32 v117, v113, v113
	v_max_f32_e32 v113, 0, v118
	v_mul_f32_e32 v118, v114, v114
	v_max_f32_e32 v114, 0, v119
	v_mul_f32_e32 v116, v116, v116
	v_mul_f32_e32 v112, v112, v112
	v_mul_f32_e32 v113, v113, v113
	v_mul_f32_e32 v114, v114, v114
	v_mul_f32_e32 v115, v115, v115
	v_cvt_pk_bf16_f32 v112, v116, v112
	v_cvt_pk_bf16_f32 v113, v113, v114
	v_cvt_pk_bf16_f32 v114, v120, v117
	v_cvt_pk_bf16_f32 v115, v118, v115
	global_store_dwordx4 v[160:161], v[112:115], off offset:256 nt
	v_mov_b32_e32 v116, 0
	s_nop 0
	v_or_b32_e32 v112, 16, v148
	v_ashrrev_i32_e32 v113, 31, v112
	v_lshlrev_b64 v[114:115], 7, v[112:113]
	v_lshl_add_u64 v[114:115], s[52:53], 0, v[114:115]
	v_lshl_add_u64 v[114:115], v[136:137], 4, v[114:115]
	s_and_saveexec_b64 s[68:69], s[14:15]
	s_cbranch_execz .LBB0_1794
	global_load_dwordx4 v[116:119], v[114:115], off
	s_waitcnt vmcnt(0)
	v_mov_b32_e32 v120, v117
	v_mov_b32_e32 v121, v118
	v_mov_b32_e32 v117, v119
	v_pk_add_f32 v[116:117], v[120:121], v[116:117]
	s_nop 0
	v_add_f32_e32 v116, v116, v117
	v_add_f32_e32 v116, 0, v116

.LBB0_1796:
	s_or_b64 exec, exec, s[68:69]
	ds_bpermute_b32 v114, v153, v116
	v_lshlrev_b64 v[112:113], 14, v[112:113]
	v_lshl_add_u64 v[112:113], s[50:51], 0, v[112:113]
	v_lshl_add_u64 v[112:113], v[146:147], 1, v[112:113]
	s_waitcnt lgkmcnt(0)
	v_add_f32_e32 v114, v116, v114
	ds_bpermute_b32 v115, v154, v114
	s_waitcnt lgkmcnt(0)
	v_add_f32_e32 v114, v114, v115
	v_fmamk_f32 v114, v114, 0x3a000000, v158
	v_rsq_f32_e32 v114, v114
	s_nop 0
	v_pk_mul_f32 v[108:109], v[108:109], v[114:115] op_sel_hi:[1,0]
	v_pk_mul_f32 v[106:107], v[106:107], v[114:115] op_sel_hi:[1,0]
	v_pk_mul_f32 v[104:105], v[104:105], v[114:115] op_sel_hi:[1,0]
	v_pk_mul_f32 v[110:111], v[110:111], v[114:115] op_sel_hi:[1,0]
	v_max_f32_e32 v104, 0, v104
	v_max_f32_e32 v109, 0, v109
	v_max_f32_e32 v105, 0, v105
	v_max_f32_e32 v106, 0, v106
	v_max_f32_e32 v108, 0, v108
	v_mul_f32_e32 v115, v104, v104
	v_mul_f32_e32 v104, v109, v109
	v_mul_f32_e32 v109, v105, v105
	v_max_f32_e32 v105, 0, v110
	v_mul_f32_e32 v110, v106, v106
	v_max_f32_e32 v106, 0, v111
	v_max_f32_e32 v107, 0, v107
	v_mul_f32_e32 v108, v108, v108
	v_mul_f32_e32 v105, v105, v105
	v_mul_f32_e32 v106, v106, v106
	v_mul_f32_e32 v107, v107, v107
	v_pk_mul_f32 v[98:99], v[98:99], v[114:115] op_sel_hi:[1,0]
	v_pk_mul_f32 v[96:97], v[96:97], v[114:115] op_sel_hi:[1,0]
	v_cvt_pk_bf16_f32 v104, v108, v104
	v_cvt_pk_bf16_f32 v105, v105, v106
	v_cvt_pk_bf16_f32 v106, v115, v109
	v_cvt_pk_bf16_f32 v107, v110, v107
	v_pk_mul_f32 v[102:103], v[102:103], v[114:115] op_sel_hi:[1,0]
	v_pk_mul_f32 v[100:101], v[100:101], v[114:115] op_sel_hi:[1,0]
	v_max_f32_e32 v96, 0, v96
	v_max_f32_e32 v97, 0, v97
	v_max_f32_e32 v98, 0, v98
	global_store_dwordx4 v[112:113], v[104:107], off nt
	v_max_f32_e32 v100, 0, v100
	v_max_f32_e32 v99, 0, v99
	v_mul_f32_e32 v104, v96, v96
	v_max_f32_e32 v96, 0, v101
	v_mul_f32_e32 v101, v97, v97
	v_max_f32_e32 v97, 0, v102
	v_mul_f32_e32 v102, v98, v98
	v_max_f32_e32 v98, 0, v103
	v_mul_f32_e32 v100, v100, v100
	v_mul_f32_e32 v96, v96, v96
	v_mul_f32_e32 v97, v97, v97
	v_mul_f32_e32 v98, v98, v98
	v_mul_f32_e32 v99, v99, v99
	v_cvt_pk_bf16_f32 v96, v100, v96
	v_cvt_pk_bf16_f32 v97, v97, v98
	v_cvt_pk_bf16_f32 v98, v104, v101
	v_cvt_pk_bf16_f32 v99, v102, v99
	global_store_dwordx4 v[112:113], v[96:99], off offset:256 nt
	v_mov_b32_e32 v100, 0
	s_nop 0
	v_or_b32_e32 v96, 32, v148
	v_ashrrev_i32_e32 v97, 31, v96
	v_lshlrev_b64 v[98:99], 7, v[96:97]
	v_lshl_add_u64 v[98:99], s[52:53], 0, v[98:99]
	v_lshl_add_u64 v[98:99], v[136:137], 4, v[98:99]
	s_and_saveexec_b64 s[68:69], s[14:15]
	s_cbranch_execz .LBB0_1798
	global_load_dwordx4 v[100:103], v[98:99], off
	s_waitcnt vmcnt(0)
	v_mov_b32_e32 v104, v101
	v_mov_b32_e32 v105, v102
	v_mov_b32_e32 v101, v103
	v_pk_add_f32 v[100:101], v[104:105], v[100:101]
	s_nop 0
	v_add_f32_e32 v100, v100, v101
	v_add_f32_e32 v100, 0, v100

.LBB0_1800:
	s_or_b64 exec, exec, s[68:69]
	ds_bpermute_b32 v98, v153, v100
	v_lshlrev_b64 v[96:97], 14, v[96:97]
	v_lshl_add_u64 v[96:97], s[50:51], 0, v[96:97]
	v_lshl_add_u64 v[96:97], v[146:147], 1, v[96:97]
	s_waitcnt lgkmcnt(0)
	v_add_f32_e32 v98, v100, v98
	ds_bpermute_b32 v99, v154, v98
	s_waitcnt lgkmcnt(0)
	v_add_f32_e32 v98, v98, v99
	v_fmamk_f32 v98, v98, 0x3a000000, v158
	v_rsq_f32_e32 v98, v98
	s_nop 0
	v_pk_mul_f32 v[92:93], v[92:93], v[98:99] op_sel_hi:[1,0]
	v_pk_mul_f32 v[90:91], v[90:91], v[98:99] op_sel_hi:[1,0]
	v_pk_mul_f32 v[88:89], v[88:89], v[98:99] op_sel_hi:[1,0]
	v_pk_mul_f32 v[94:95], v[94:95], v[98:99] op_sel_hi:[1,0]
	v_max_f32_e32 v88, 0, v88
	v_max_f32_e32 v93, 0, v93
	v_max_f32_e32 v89, 0, v89
	v_max_f32_e32 v90, 0, v90
	v_max_f32_e32 v92, 0, v92
	v_mul_f32_e32 v99, v88, v88
	v_mul_f32_e32 v88, v93, v93
	v_mul_f32_e32 v93, v89, v89
	v_max_f32_e32 v89, 0, v94
	v_mul_f32_e32 v94, v90, v90
	v_max_f32_e32 v90, 0, v95
	v_max_f32_e32 v91, 0, v91
	v_mul_f32_e32 v92, v92, v92
	v_mul_f32_e32 v89, v89, v89
	v_mul_f32_e32 v90, v90, v90
	v_mul_f32_e32 v91, v91, v91
	v_pk_mul_f32 v[82:83], v[82:83], v[98:99] op_sel_hi:[1,0]
	v_pk_mul_f32 v[80:81], v[80:81], v[98:99] op_sel_hi:[1,0]
	v_cvt_pk_bf16_f32 v88, v92, v88
	v_cvt_pk_bf16_f32 v89, v89, v90
	v_cvt_pk_bf16_f32 v90, v99, v93
	v_cvt_pk_bf16_f32 v91, v94, v91
	v_pk_mul_f32 v[86:87], v[86:87], v[98:99] op_sel_hi:[1,0]
	v_pk_mul_f32 v[84:85], v[84:85], v[98:99] op_sel_hi:[1,0]
	v_max_f32_e32 v80, 0, v80
	v_max_f32_e32 v81, 0, v81
	v_max_f32_e32 v82, 0, v82
	global_store_dwordx4 v[96:97], v[88:91], off nt
	v_max_f32_e32 v84, 0, v84
	v_max_f32_e32 v83, 0, v83
	v_mul_f32_e32 v88, v80, v80
	v_max_f32_e32 v80, 0, v85
	v_mul_f32_e32 v85, v81, v81
	v_max_f32_e32 v81, 0, v86
	v_mul_f32_e32 v86, v82, v82
	v_max_f32_e32 v82, 0, v87
	v_mul_f32_e32 v84, v84, v84
	v_mul_f32_e32 v80, v80, v80
	v_mul_f32_e32 v81, v81, v81
	v_mul_f32_e32 v82, v82, v82
	v_mul_f32_e32 v83, v83, v83
	v_cvt_pk_bf16_f32 v80, v84, v80
	v_cvt_pk_bf16_f32 v81, v81, v82
	v_cvt_pk_bf16_f32 v82, v88, v85
	v_cvt_pk_bf16_f32 v83, v86, v83
	global_store_dwordx4 v[96:97], v[80:83], off offset:256 nt
	v_mov_b32_e32 v84, 0
	s_nop 0
	v_or_b32_e32 v80, 48, v148
	v_ashrrev_i32_e32 v81, 31, v80
	v_lshlrev_b64 v[82:83], 7, v[80:81]
	v_lshl_add_u64 v[82:83], s[52:53], 0, v[82:83]
	v_lshl_add_u64 v[82:83], v[136:137], 4, v[82:83]
	s_and_saveexec_b64 s[68:69], s[14:15]
	s_cbranch_execz .LBB0_1802
	global_load_dwordx4 v[84:87], v[82:83], off
	s_waitcnt vmcnt(0)
	v_mov_b32_e32 v88, v85
	v_mov_b32_e32 v89, v86
	v_mov_b32_e32 v85, v87
	v_pk_add_f32 v[84:85], v[88:89], v[84:85]
	s_nop 0
	v_add_f32_e32 v84, v84, v85
	v_add_f32_e32 v84, 0, v84

.LBB0_1804:
	s_or_b64 exec, exec, s[68:69]
	ds_bpermute_b32 v82, v153, v84
	v_lshlrev_b64 v[80:81], 14, v[80:81]
	v_lshl_add_u64 v[80:81], s[50:51], 0, v[80:81]
	v_lshl_add_u64 v[80:81], v[146:147], 1, v[80:81]
	s_waitcnt lgkmcnt(0)
	v_add_f32_e32 v82, v84, v82
	ds_bpermute_b32 v83, v154, v82
	s_waitcnt lgkmcnt(0)
	v_add_f32_e32 v82, v82, v83
	v_fmamk_f32 v82, v82, 0x3a000000, v158
	v_rsq_f32_e32 v82, v82
	s_nop 0
	v_pk_mul_f32 v[76:77], v[76:77], v[82:83] op_sel_hi:[1,0]
	v_pk_mul_f32 v[74:75], v[74:75], v[82:83] op_sel_hi:[1,0]
	v_pk_mul_f32 v[72:73], v[72:73], v[82:83] op_sel_hi:[1,0]
	v_pk_mul_f32 v[78:79], v[78:79], v[82:83] op_sel_hi:[1,0]
	v_max_f32_e32 v72, 0, v72
	v_max_f32_e32 v77, 0, v77
	v_max_f32_e32 v73, 0, v73
	v_max_f32_e32 v74, 0, v74
	v_max_f32_e32 v76, 0, v76
	v_mul_f32_e32 v83, v72, v72
	v_mul_f32_e32 v72, v77, v77
	v_mul_f32_e32 v77, v73, v73
	v_max_f32_e32 v73, 0, v78
	v_mul_f32_e32 v78, v74, v74
	v_max_f32_e32 v74, 0, v79
	v_max_f32_e32 v75, 0, v75
	v_mul_f32_e32 v76, v76, v76
	v_mul_f32_e32 v73, v73, v73
	v_mul_f32_e32 v74, v74, v74
	v_mul_f32_e32 v75, v75, v75
	v_pk_mul_f32 v[66:67], v[66:67], v[82:83] op_sel_hi:[1,0]
	v_pk_mul_f32 v[64:65], v[64:65], v[82:83] op_sel_hi:[1,0]
	v_cvt_pk_bf16_f32 v72, v76, v72
	v_cvt_pk_bf16_f32 v73, v73, v74
	v_cvt_pk_bf16_f32 v74, v83, v77
	v_cvt_pk_bf16_f32 v75, v78, v75
	v_pk_mul_f32 v[70:71], v[70:71], v[82:83] op_sel_hi:[1,0]
	v_pk_mul_f32 v[68:69], v[68:69], v[82:83] op_sel_hi:[1,0]
	v_max_f32_e32 v64, 0, v64
	v_max_f32_e32 v65, 0, v65
	v_max_f32_e32 v66, 0, v66
	global_store_dwordx4 v[80:81], v[72:75], off nt
	v_max_f32_e32 v68, 0, v68
	v_max_f32_e32 v67, 0, v67
	v_mul_f32_e32 v72, v64, v64
	v_max_f32_e32 v64, 0, v69
	v_mul_f32_e32 v69, v65, v65
	v_max_f32_e32 v65, 0, v70
	v_mul_f32_e32 v70, v66, v66
	v_max_f32_e32 v66, 0, v71
	v_mul_f32_e32 v68, v68, v68
	v_mul_f32_e32 v64, v64, v64
	v_mul_f32_e32 v65, v65, v65
	v_mul_f32_e32 v66, v66, v66
	v_mul_f32_e32 v67, v67, v67
	v_cvt_pk_bf16_f32 v64, v68, v64
	v_cvt_pk_bf16_f32 v65, v65, v66
	v_cvt_pk_bf16_f32 v66, v72, v69
	v_cvt_pk_bf16_f32 v67, v70, v67
	global_store_dwordx4 v[80:81], v[64:67], off offset:256 nt
	v_mov_b32_e32 v68, 0
	s_nop 0
	v_add_u32_e32 v64, 0x80, v148
	v_ashrrev_i32_e32 v65, 31, v64
	v_lshlrev_b64 v[66:67], 7, v[64:65]
	v_lshl_add_u64 v[66:67], s[52:53], 0, v[66:67]
	v_lshl_add_u64 v[66:67], v[136:137], 4, v[66:67]
	s_and_saveexec_b64 s[68:69], s[14:15]
	s_cbranch_execz .LBB0_1806
	global_load_dwordx4 v[68:71], v[66:67], off
	s_waitcnt vmcnt(0)
	v_mov_b32_e32 v72, v69
	v_mov_b32_e32 v73, v70
	v_mov_b32_e32 v69, v71
	v_pk_add_f32 v[68:69], v[72:73], v[68:69]
	s_nop 0
	v_add_f32_e32 v68, v68, v69
	v_add_f32_e32 v68, 0, v68

.LBB0_1808:
	s_or_b64 exec, exec, s[68:69]
	ds_bpermute_b32 v66, v153, v68
	v_lshlrev_b64 v[64:65], 14, v[64:65]
	v_lshl_add_u64 v[64:65], s[50:51], 0, v[64:65]
	v_lshl_add_u64 v[64:65], v[146:147], 1, v[64:65]
	s_waitcnt lgkmcnt(0)
	v_add_f32_e32 v66, v68, v66
	ds_bpermute_b32 v67, v154, v66
	s_waitcnt lgkmcnt(0)
	v_add_f32_e32 v66, v66, v67
	v_fmamk_f32 v66, v66, 0x3a000000, v158
	v_rsq_f32_e32 v66, v66
	s_nop 0
	v_pk_mul_f32 v[60:61], v[60:61], v[66:67] op_sel_hi:[1,0]
	v_pk_mul_f32 v[58:59], v[58:59], v[66:67] op_sel_hi:[1,0]
	v_pk_mul_f32 v[56:57], v[56:57], v[66:67] op_sel_hi:[1,0]
	v_pk_mul_f32 v[62:63], v[62:63], v[66:67] op_sel_hi:[1,0]
	v_max_f32_e32 v56, 0, v56
	v_max_f32_e32 v61, 0, v61
	v_max_f32_e32 v57, 0, v57
	v_max_f32_e32 v58, 0, v58
	v_max_f32_e32 v60, 0, v60
	v_mul_f32_e32 v67, v56, v56
	v_mul_f32_e32 v56, v61, v61
	v_mul_f32_e32 v61, v57, v57
	v_max_f32_e32 v57, 0, v62
	v_mul_f32_e32 v62, v58, v58
	v_max_f32_e32 v58, 0, v63
	v_max_f32_e32 v59, 0, v59
	v_mul_f32_e32 v60, v60, v60
	v_mul_f32_e32 v57, v57, v57
	v_mul_f32_e32 v58, v58, v58
	v_mul_f32_e32 v59, v59, v59
	v_pk_mul_f32 v[50:51], v[50:51], v[66:67] op_sel_hi:[1,0]
	v_pk_mul_f32 v[48:49], v[48:49], v[66:67] op_sel_hi:[1,0]
	v_cvt_pk_bf16_f32 v56, v60, v56
	v_cvt_pk_bf16_f32 v57, v57, v58
	v_cvt_pk_bf16_f32 v58, v67, v61
	v_cvt_pk_bf16_f32 v59, v62, v59
	v_pk_mul_f32 v[54:55], v[54:55], v[66:67] op_sel_hi:[1,0]
	v_pk_mul_f32 v[52:53], v[52:53], v[66:67] op_sel_hi:[1,0]
	v_max_f32_e32 v48, 0, v48
	v_max_f32_e32 v49, 0, v49
	v_max_f32_e32 v50, 0, v50
	global_store_dwordx4 v[64:65], v[56:59], off nt
	v_max_f32_e32 v52, 0, v52
	v_max_f32_e32 v51, 0, v51
	v_mul_f32_e32 v56, v48, v48
	v_max_f32_e32 v48, 0, v53
	v_mul_f32_e32 v53, v49, v49
	v_max_f32_e32 v49, 0, v54
	v_mul_f32_e32 v54, v50, v50
	v_max_f32_e32 v50, 0, v55
	v_mul_f32_e32 v52, v52, v52
	v_mul_f32_e32 v48, v48, v48
	v_mul_f32_e32 v49, v49, v49
	v_mul_f32_e32 v50, v50, v50
	v_mul_f32_e32 v51, v51, v51
	v_cvt_pk_bf16_f32 v48, v52, v48
	v_cvt_pk_bf16_f32 v49, v49, v50
	v_cvt_pk_bf16_f32 v50, v56, v53
	v_cvt_pk_bf16_f32 v51, v54, v51
	global_store_dwordx4 v[64:65], v[48:51], off offset:256 nt
	v_mov_b32_e32 v52, 0
	s_nop 0
	v_add_u32_e32 v48, 0x90, v148
	v_ashrrev_i32_e32 v49, 31, v48
	v_lshlrev_b64 v[50:51], 7, v[48:49]
	v_lshl_add_u64 v[50:51], s[52:53], 0, v[50:51]
	v_lshl_add_u64 v[50:51], v[136:137], 4, v[50:51]
	s_and_saveexec_b64 s[68:69], s[14:15]
	s_cbranch_execz .LBB0_1810
	global_load_dwordx4 v[52:55], v[50:51], off
	s_waitcnt vmcnt(0)
	v_mov_b32_e32 v56, v53
	v_mov_b32_e32 v57, v54
	v_mov_b32_e32 v53, v55
	v_pk_add_f32 v[52:53], v[56:57], v[52:53]
	s_nop 0
	v_add_f32_e32 v52, v52, v53
	v_add_f32_e32 v52, 0, v52

.LBB0_1812:
	s_or_b64 exec, exec, s[68:69]
	ds_bpermute_b32 v50, v153, v52
	v_lshlrev_b64 v[48:49], 14, v[48:49]
	v_lshl_add_u64 v[48:49], s[50:51], 0, v[48:49]
	v_lshl_add_u64 v[48:49], v[146:147], 1, v[48:49]
	s_waitcnt lgkmcnt(0)
	v_add_f32_e32 v50, v52, v50
	ds_bpermute_b32 v51, v154, v50
	s_waitcnt lgkmcnt(0)
	v_add_f32_e32 v50, v50, v51
	v_fmamk_f32 v50, v50, 0x3a000000, v158
	v_rsq_f32_e32 v50, v50
	s_nop 0
	v_pk_mul_f32 v[44:45], v[44:45], v[50:51] op_sel_hi:[1,0]
	v_pk_mul_f32 v[42:43], v[42:43], v[50:51] op_sel_hi:[1,0]
	v_pk_mul_f32 v[40:41], v[40:41], v[50:51] op_sel_hi:[1,0]
	v_pk_mul_f32 v[46:47], v[46:47], v[50:51] op_sel_hi:[1,0]
	v_max_f32_e32 v40, 0, v40
	v_max_f32_e32 v45, 0, v45
	v_max_f32_e32 v41, 0, v41
	v_max_f32_e32 v42, 0, v42
	v_max_f32_e32 v44, 0, v44
	v_mul_f32_e32 v51, v40, v40
	v_mul_f32_e32 v40, v45, v45
	v_mul_f32_e32 v45, v41, v41
	v_max_f32_e32 v41, 0, v46
	v_mul_f32_e32 v46, v42, v42
	v_max_f32_e32 v42, 0, v47
	v_max_f32_e32 v43, 0, v43
	v_mul_f32_e32 v44, v44, v44
	v_mul_f32_e32 v41, v41, v41
	v_mul_f32_e32 v42, v42, v42
	v_mul_f32_e32 v43, v43, v43
	v_pk_mul_f32 v[34:35], v[34:35], v[50:51] op_sel_hi:[1,0]
	v_pk_mul_f32 v[32:33], v[32:33], v[50:51] op_sel_hi:[1,0]
	v_cvt_pk_bf16_f32 v40, v44, v40
	v_cvt_pk_bf16_f32 v41, v41, v42
	v_cvt_pk_bf16_f32 v42, v51, v45
	v_cvt_pk_bf16_f32 v43, v46, v43
	v_pk_mul_f32 v[38:39], v[38:39], v[50:51] op_sel_hi:[1,0]
	v_pk_mul_f32 v[36:37], v[36:37], v[50:51] op_sel_hi:[1,0]
	v_max_f32_e32 v32, 0, v32
	v_max_f32_e32 v33, 0, v33
	v_max_f32_e32 v34, 0, v34
	global_store_dwordx4 v[48:49], v[40:43], off nt
	v_max_f32_e32 v36, 0, v36
	v_max_f32_e32 v35, 0, v35
	v_mul_f32_e32 v40, v32, v32
	v_max_f32_e32 v32, 0, v37
	v_mul_f32_e32 v37, v33, v33
	v_max_f32_e32 v33, 0, v38
	v_mul_f32_e32 v38, v34, v34
	v_max_f32_e32 v34, 0, v39
	v_mul_f32_e32 v36, v36, v36
	v_mul_f32_e32 v32, v32, v32
	v_mul_f32_e32 v33, v33, v33
	v_mul_f32_e32 v34, v34, v34
	v_mul_f32_e32 v35, v35, v35
	v_cvt_pk_bf16_f32 v32, v36, v32
	v_cvt_pk_bf16_f32 v33, v33, v34
	v_cvt_pk_bf16_f32 v34, v40, v37
	v_cvt_pk_bf16_f32 v35, v38, v35
	global_store_dwordx4 v[48:49], v[32:35], off offset:256 nt
	v_mov_b32_e32 v36, 0
	s_nop 0
	v_add_u32_e32 v32, 0xa0, v148
	v_ashrrev_i32_e32 v33, 31, v32
	v_lshlrev_b64 v[34:35], 7, v[32:33]
	v_lshl_add_u64 v[34:35], s[52:53], 0, v[34:35]
	v_lshl_add_u64 v[34:35], v[136:137], 4, v[34:35]
	s_and_saveexec_b64 s[68:69], s[14:15]
	s_cbranch_execz .LBB0_1814
	global_load_dwordx4 v[36:39], v[34:35], off
	s_waitcnt vmcnt(0)
	v_mov_b32_e32 v40, v37
	v_mov_b32_e32 v41, v38
	v_mov_b32_e32 v37, v39
	v_pk_add_f32 v[36:37], v[40:41], v[36:37]
	s_nop 0
	v_add_f32_e32 v36, v36, v37
	v_add_f32_e32 v36, 0, v36

.LBB0_1816:
	s_or_b64 exec, exec, s[68:69]
	ds_bpermute_b32 v34, v153, v36
	v_lshlrev_b64 v[32:33], 14, v[32:33]
	v_lshl_add_u64 v[32:33], s[50:51], 0, v[32:33]
	v_lshl_add_u64 v[32:33], v[146:147], 1, v[32:33]
	s_waitcnt lgkmcnt(0)
	v_add_f32_e32 v34, v36, v34
	ds_bpermute_b32 v35, v154, v34
	s_waitcnt lgkmcnt(0)
	v_add_f32_e32 v34, v34, v35
	v_fmamk_f32 v34, v34, 0x3a000000, v158
	v_rsq_f32_e32 v34, v34
	s_nop 0
	v_pk_mul_f32 v[28:29], v[28:29], v[34:35] op_sel_hi:[1,0]
	v_pk_mul_f32 v[26:27], v[26:27], v[34:35] op_sel_hi:[1,0]
	v_pk_mul_f32 v[24:25], v[24:25], v[34:35] op_sel_hi:[1,0]
	v_pk_mul_f32 v[30:31], v[30:31], v[34:35] op_sel_hi:[1,0]
	v_max_f32_e32 v24, 0, v24
	v_max_f32_e32 v29, 0, v29
	v_max_f32_e32 v25, 0, v25
	v_max_f32_e32 v26, 0, v26
	v_max_f32_e32 v28, 0, v28
	v_mul_f32_e32 v35, v24, v24
	v_mul_f32_e32 v24, v29, v29
	v_mul_f32_e32 v29, v25, v25
	v_max_f32_e32 v25, 0, v30
	v_mul_f32_e32 v30, v26, v26
	v_max_f32_e32 v26, 0, v31
	v_max_f32_e32 v27, 0, v27
	v_mul_f32_e32 v28, v28, v28
	v_mul_f32_e32 v25, v25, v25
	v_mul_f32_e32 v26, v26, v26
	v_mul_f32_e32 v27, v27, v27
	v_pk_mul_f32 v[18:19], v[18:19], v[34:35] op_sel_hi:[1,0]
	v_pk_mul_f32 v[16:17], v[16:17], v[34:35] op_sel_hi:[1,0]
	v_cvt_pk_bf16_f32 v24, v28, v24
	v_cvt_pk_bf16_f32 v25, v25, v26
	v_cvt_pk_bf16_f32 v26, v35, v29
	v_cvt_pk_bf16_f32 v27, v30, v27
	v_pk_mul_f32 v[22:23], v[22:23], v[34:35] op_sel_hi:[1,0]
	v_pk_mul_f32 v[20:21], v[20:21], v[34:35] op_sel_hi:[1,0]
	v_max_f32_e32 v16, 0, v16
	v_max_f32_e32 v17, 0, v17
	v_max_f32_e32 v18, 0, v18
	global_store_dwordx4 v[32:33], v[24:27], off nt
	v_max_f32_e32 v20, 0, v20
	v_max_f32_e32 v19, 0, v19
	v_mul_f32_e32 v24, v16, v16
	v_max_f32_e32 v16, 0, v21
	v_mul_f32_e32 v21, v17, v17
	v_max_f32_e32 v17, 0, v22
	v_mul_f32_e32 v22, v18, v18
	v_max_f32_e32 v18, 0, v23
	v_mul_f32_e32 v20, v20, v20
	v_mul_f32_e32 v16, v16, v16
	v_mul_f32_e32 v17, v17, v17
	v_mul_f32_e32 v18, v18, v18
	v_mul_f32_e32 v19, v19, v19
	v_cvt_pk_bf16_f32 v16, v20, v16
	v_cvt_pk_bf16_f32 v17, v17, v18
	v_cvt_pk_bf16_f32 v18, v24, v21
	v_cvt_pk_bf16_f32 v19, v22, v19
	global_store_dwordx4 v[32:33], v[16:19], off offset:256 nt
	v_mov_b32_e32 v20, 0
	s_nop 0
	v_add_u32_e32 v16, 0xb0, v148
	v_ashrrev_i32_e32 v17, 31, v16
	v_lshlrev_b64 v[18:19], 7, v[16:17]
	v_lshl_add_u64 v[18:19], s[52:53], 0, v[18:19]
	v_lshl_add_u64 v[18:19], v[136:137], 4, v[18:19]
	s_and_saveexec_b64 s[68:69], s[14:15]
	s_cbranch_execz .LBB0_1818
	global_load_dwordx4 v[20:23], v[18:19], off
	s_waitcnt vmcnt(0)
	v_mov_b32_e32 v24, v21
	v_mov_b32_e32 v25, v22
	v_mov_b32_e32 v21, v23
	v_pk_add_f32 v[20:21], v[24:25], v[20:21]
	s_nop 0
	v_add_f32_e32 v20, v20, v21
	v_add_f32_e32 v20, 0, v20

.LBB0_1820:
	s_or_b64 exec, exec, s[68:69]
	ds_bpermute_b32 v18, v153, v20
	v_lshlrev_b64 v[16:17], 14, v[16:17]
	v_lshl_add_u64 v[16:17], s[50:51], 0, v[16:17]
	v_lshl_add_u64 v[16:17], v[146:147], 1, v[16:17]
	s_andn2_b64 vcc, exec, s[18:19]
	s_waitcnt lgkmcnt(0)
	v_add_f32_e32 v18, v20, v18
	ds_bpermute_b32 v19, v154, v18
	s_mov_b64 s[18:19], -1
	s_waitcnt lgkmcnt(0)
	v_add_f32_e32 v18, v18, v19
	v_fmamk_f32 v18, v18, 0x3a000000, v158
	v_rsq_f32_e32 v18, v18
	s_nop 0
	v_pk_mul_f32 v[12:13], v[12:13], v[18:19] op_sel_hi:[1,0]
	v_pk_mul_f32 v[10:11], v[10:11], v[18:19] op_sel_hi:[1,0]
	v_pk_mul_f32 v[8:9], v[8:9], v[18:19] op_sel_hi:[1,0]
	v_pk_mul_f32 v[14:15], v[14:15], v[18:19] op_sel_hi:[1,0]
	v_max_f32_e32 v8, 0, v8
	v_max_f32_e32 v13, 0, v13
	v_max_f32_e32 v9, 0, v9
	v_max_f32_e32 v10, 0, v10
	v_max_f32_e32 v12, 0, v12
	v_mul_f32_e32 v19, v8, v8
	v_mul_f32_e32 v8, v13, v13
	v_mul_f32_e32 v13, v9, v9
	v_max_f32_e32 v9, 0, v14
	v_mul_f32_e32 v14, v10, v10
	v_max_f32_e32 v10, 0, v15
	v_max_f32_e32 v11, 0, v11
	v_mul_f32_e32 v12, v12, v12
	v_mul_f32_e32 v9, v9, v9
	v_mul_f32_e32 v10, v10, v10
	v_mul_f32_e32 v11, v11, v11
	v_pk_mul_f32 v[2:3], v[2:3], v[18:19] op_sel_hi:[1,0]
	v_pk_mul_f32 v[0:1], v[0:1], v[18:19] op_sel_hi:[1,0]
	v_cvt_pk_bf16_f32 v8, v12, v8
	v_cvt_pk_bf16_f32 v9, v9, v10
	v_cvt_pk_bf16_f32 v10, v19, v13
	v_cvt_pk_bf16_f32 v11, v14, v11
	v_pk_mul_f32 v[6:7], v[6:7], v[18:19] op_sel_hi:[1,0]
	v_pk_mul_f32 v[4:5], v[4:5], v[18:19] op_sel_hi:[1,0]
	v_max_f32_e32 v0, 0, v0
	v_max_f32_e32 v1, 0, v1
	v_max_f32_e32 v2, 0, v2
	global_store_dwordx4 v[16:17], v[8:11], off nt
	v_max_f32_e32 v4, 0, v4
	v_max_f32_e32 v3, 0, v3
	v_mul_f32_e32 v8, v0, v0
	v_max_f32_e32 v0, 0, v5
	v_mul_f32_e32 v5, v1, v1
	v_max_f32_e32 v1, 0, v6
	v_mul_f32_e32 v6, v2, v2
	v_max_f32_e32 v2, 0, v7
	v_mul_f32_e32 v4, v4, v4
	v_mul_f32_e32 v0, v0, v0
	v_mul_f32_e32 v1, v1, v1
	v_mul_f32_e32 v2, v2, v2
	v_mul_f32_e32 v3, v3, v3
	v_cvt_pk_bf16_f32 v0, v4, v0
	v_cvt_pk_bf16_f32 v1, v1, v2
	v_cvt_pk_bf16_f32 v2, v8, v5
	v_cvt_pk_bf16_f32 v3, v6, v3
	global_store_dwordx4 v[16:17], v[0:3], off offset:256 nt
	s_cbranch_vccnz .LBB0_1777
	s_and_b64 vcc, exec, s[10:11]
	s_cbranch_vccnz .LBB0_1776
	s_barrier
	s_branch .LBB0_1776

.LBB0_2812:
	s_or_b64 exec, exec, s[44:45]
	ds_bpermute_b32 v146, v153, v159
	v_lshlrev_b64 v[160:161], 14, v[148:149]
	v_lshl_add_u64 v[160:161], s[50:51], 0, v[160:161]
	s_waitcnt lgkmcnt(0)
	v_add_f32_e32 v147, v159, v146
	ds_bpermute_b32 v159, v154, v147
	v_lshl_add_u32 v146, s42, 8, v152
	s_waitcnt lgkmcnt(0)
	v_add_f32_e32 v147, v147, v159
	v_fmamk_f32 v147, v147, 0x3a000000, v158
	v_rsq_f32_e32 v162, v147
	v_ashrrev_i32_e32 v147, 31, v146
	v_lshl_add_u64 v[160:161], v[146:147], 1, v[160:161]
	v_pk_mul_f32 v[120:121], v[120:121], v[162:163] op_sel_hi:[1,0]
	v_pk_mul_f32 v[124:125], v[124:125], v[162:163] op_sel_hi:[1,0]
	v_max_f32_e32 v120, 0, v120
	v_pk_mul_f32 v[126:127], v[126:127], v[162:163] op_sel_hi:[1,0]
	v_pk_mul_f32 v[122:123], v[122:123], v[162:163] op_sel_hi:[1,0]
	v_max_f32_e32 v125, 0, v125
	v_mul_f32_e32 v149, v120, v120
	v_max_f32_e32 v120, 0, v121
	v_mul_f32_e32 v121, v125, v125
	v_mul_f32_e32 v125, v120, v120
	v_max_f32_e32 v120, 0, v126
	v_max_f32_e32 v122, 0, v122
	v_max_f32_e32 v124, 0, v124
	v_mul_f32_e32 v126, v120, v120
	v_mul_f32_e32 v159, v122, v122
	v_max_f32_e32 v120, 0, v127
	v_max_f32_e32 v122, 0, v123
	v_mul_f32_e32 v124, v124, v124
	v_mul_f32_e32 v123, v120, v120
	v_mul_f32_e32 v127, v122, v122
	v_pk_mul_f32 v[114:115], v[114:115], v[162:163] op_sel_hi:[1,0]
	v_pk_mul_f32 v[112:113], v[112:113], v[162:163] op_sel_hi:[1,0]
	v_cvt_pk_bf16_f32 v120, v124, v121
	v_cvt_pk_bf16_f32 v121, v126, v123
	v_cvt_pk_bf16_f32 v122, v149, v125
	v_cvt_pk_bf16_f32 v123, v159, v127
	v_pk_mul_f32 v[118:119], v[118:119], v[162:163] op_sel_hi:[1,0]
	v_pk_mul_f32 v[116:117], v[116:117], v[162:163] op_sel_hi:[1,0]
	v_max_f32_e32 v112, 0, v112
	v_max_f32_e32 v113, 0, v113
	v_max_f32_e32 v114, 0, v114
	global_store_dwordx4 v[160:161], v[120:123], off nt
	v_max_f32_e32 v116, 0, v116
	v_max_f32_e32 v115, 0, v115
	v_mul_f32_e32 v120, v112, v112
	v_max_f32_e32 v112, 0, v117
	v_mul_f32_e32 v117, v113, v113
	v_max_f32_e32 v113, 0, v118
	v_mul_f32_e32 v118, v114, v114
	v_max_f32_e32 v114, 0, v119
	v_mul_f32_e32 v116, v116, v116
	v_mul_f32_e32 v112, v112, v112
	v_mul_f32_e32 v113, v113, v113
	v_mul_f32_e32 v114, v114, v114
	v_mul_f32_e32 v115, v115, v115
	v_cvt_pk_bf16_f32 v112, v116, v112
	v_cvt_pk_bf16_f32 v113, v113, v114
	v_cvt_pk_bf16_f32 v114, v120, v117
	v_cvt_pk_bf16_f32 v115, v118, v115
	global_store_dwordx4 v[160:161], v[112:115], off offset:256 nt
	v_mov_b32_e32 v116, 0
	s_nop 0
	v_or_b32_e32 v112, 16, v148
	v_ashrrev_i32_e32 v113, 31, v112
	v_lshlrev_b64 v[114:115], 7, v[112:113]
	v_lshl_add_u64 v[114:115], s[52:53], 0, v[114:115]
	v_lshl_add_u64 v[114:115], v[136:137], 4, v[114:115]
	s_and_saveexec_b64 s[42:43], s[6:7]
	s_cbranch_execz .LBB0_2814
	global_load_dwordx4 v[116:119], v[114:115], off
	s_waitcnt vmcnt(0)
	v_mov_b32_e32 v120, v117
	v_mov_b32_e32 v121, v118
	v_mov_b32_e32 v117, v119
	v_pk_add_f32 v[116:117], v[120:121], v[116:117]
	s_nop 0
	v_add_f32_e32 v116, v116, v117
	v_add_f32_e32 v116, 0, v116

.LBB0_2816:
	s_or_b64 exec, exec, s[42:43]
	ds_bpermute_b32 v114, v153, v116
	v_lshlrev_b64 v[112:113], 14, v[112:113]
	v_lshl_add_u64 v[112:113], s[50:51], 0, v[112:113]
	v_lshl_add_u64 v[112:113], v[146:147], 1, v[112:113]
	s_waitcnt lgkmcnt(0)
	v_add_f32_e32 v114, v116, v114
	ds_bpermute_b32 v115, v154, v114
	s_waitcnt lgkmcnt(0)
	v_add_f32_e32 v114, v114, v115
	v_fmamk_f32 v114, v114, 0x3a000000, v158
	v_rsq_f32_e32 v114, v114
	s_nop 0
	v_pk_mul_f32 v[108:109], v[108:109], v[114:115] op_sel_hi:[1,0]
	v_pk_mul_f32 v[106:107], v[106:107], v[114:115] op_sel_hi:[1,0]
	v_pk_mul_f32 v[104:105], v[104:105], v[114:115] op_sel_hi:[1,0]
	v_pk_mul_f32 v[110:111], v[110:111], v[114:115] op_sel_hi:[1,0]
	v_max_f32_e32 v104, 0, v104
	v_max_f32_e32 v109, 0, v109
	v_max_f32_e32 v105, 0, v105
	v_max_f32_e32 v106, 0, v106
	v_max_f32_e32 v108, 0, v108
	v_mul_f32_e32 v115, v104, v104
	v_mul_f32_e32 v104, v109, v109
	v_mul_f32_e32 v109, v105, v105
	v_max_f32_e32 v105, 0, v110
	v_mul_f32_e32 v110, v106, v106
	v_max_f32_e32 v106, 0, v111
	v_max_f32_e32 v107, 0, v107
	v_mul_f32_e32 v108, v108, v108
	v_mul_f32_e32 v105, v105, v105
	v_mul_f32_e32 v106, v106, v106
	v_mul_f32_e32 v107, v107, v107
	v_pk_mul_f32 v[98:99], v[98:99], v[114:115] op_sel_hi:[1,0]
	v_pk_mul_f32 v[96:97], v[96:97], v[114:115] op_sel_hi:[1,0]
	v_cvt_pk_bf16_f32 v104, v108, v104
	v_cvt_pk_bf16_f32 v105, v105, v106
	v_cvt_pk_bf16_f32 v106, v115, v109
	v_cvt_pk_bf16_f32 v107, v110, v107
	v_pk_mul_f32 v[102:103], v[102:103], v[114:115] op_sel_hi:[1,0]
	v_pk_mul_f32 v[100:101], v[100:101], v[114:115] op_sel_hi:[1,0]
	v_max_f32_e32 v96, 0, v96
	v_max_f32_e32 v97, 0, v97
	v_max_f32_e32 v98, 0, v98
	global_store_dwordx4 v[112:113], v[104:107], off nt
	v_max_f32_e32 v100, 0, v100
	v_max_f32_e32 v99, 0, v99
	v_mul_f32_e32 v104, v96, v96
	v_max_f32_e32 v96, 0, v101
	v_mul_f32_e32 v101, v97, v97
	v_max_f32_e32 v97, 0, v102
	v_mul_f32_e32 v102, v98, v98
	v_max_f32_e32 v98, 0, v103
	v_mul_f32_e32 v100, v100, v100
	v_mul_f32_e32 v96, v96, v96
	v_mul_f32_e32 v97, v97, v97
	v_mul_f32_e32 v98, v98, v98
	v_mul_f32_e32 v99, v99, v99
	v_cvt_pk_bf16_f32 v96, v100, v96
	v_cvt_pk_bf16_f32 v97, v97, v98
	v_cvt_pk_bf16_f32 v98, v104, v101
	v_cvt_pk_bf16_f32 v99, v102, v99
	global_store_dwordx4 v[112:113], v[96:99], off offset:256 nt
	v_mov_b32_e32 v100, 0
	s_nop 0
	v_or_b32_e32 v96, 32, v148
	v_ashrrev_i32_e32 v97, 31, v96
	v_lshlrev_b64 v[98:99], 7, v[96:97]
	v_lshl_add_u64 v[98:99], s[52:53], 0, v[98:99]
	v_lshl_add_u64 v[98:99], v[136:137], 4, v[98:99]
	s_and_saveexec_b64 s[42:43], s[6:7]
	s_cbranch_execz .LBB0_2818
	global_load_dwordx4 v[100:103], v[98:99], off
	s_waitcnt vmcnt(0)
	v_mov_b32_e32 v104, v101
	v_mov_b32_e32 v105, v102
	v_mov_b32_e32 v101, v103
	v_pk_add_f32 v[100:101], v[104:105], v[100:101]
	s_nop 0
	v_add_f32_e32 v100, v100, v101
	v_add_f32_e32 v100, 0, v100

.LBB0_2820:
	s_or_b64 exec, exec, s[42:43]
	ds_bpermute_b32 v98, v153, v100
	v_lshlrev_b64 v[96:97], 14, v[96:97]
	v_lshl_add_u64 v[96:97], s[50:51], 0, v[96:97]
	v_lshl_add_u64 v[96:97], v[146:147], 1, v[96:97]
	s_waitcnt lgkmcnt(0)
	v_add_f32_e32 v98, v100, v98
	ds_bpermute_b32 v99, v154, v98
	s_waitcnt lgkmcnt(0)
	v_add_f32_e32 v98, v98, v99
	v_fmamk_f32 v98, v98, 0x3a000000, v158
	v_rsq_f32_e32 v98, v98
	s_nop 0
	v_pk_mul_f32 v[92:93], v[92:93], v[98:99] op_sel_hi:[1,0]
	v_pk_mul_f32 v[90:91], v[90:91], v[98:99] op_sel_hi:[1,0]
	v_pk_mul_f32 v[88:89], v[88:89], v[98:99] op_sel_hi:[1,0]
	v_pk_mul_f32 v[94:95], v[94:95], v[98:99] op_sel_hi:[1,0]
	v_max_f32_e32 v88, 0, v88
	v_max_f32_e32 v93, 0, v93
	v_max_f32_e32 v89, 0, v89
	v_max_f32_e32 v90, 0, v90
	v_max_f32_e32 v92, 0, v92
	v_mul_f32_e32 v99, v88, v88
	v_mul_f32_e32 v88, v93, v93
	v_mul_f32_e32 v93, v89, v89
	v_max_f32_e32 v89, 0, v94
	v_mul_f32_e32 v94, v90, v90
	v_max_f32_e32 v90, 0, v95
	v_max_f32_e32 v91, 0, v91
	v_mul_f32_e32 v92, v92, v92
	v_mul_f32_e32 v89, v89, v89
	v_mul_f32_e32 v90, v90, v90
	v_mul_f32_e32 v91, v91, v91
	v_pk_mul_f32 v[82:83], v[82:83], v[98:99] op_sel_hi:[1,0]
	v_pk_mul_f32 v[80:81], v[80:81], v[98:99] op_sel_hi:[1,0]
	v_cvt_pk_bf16_f32 v88, v92, v88
	v_cvt_pk_bf16_f32 v89, v89, v90
	v_cvt_pk_bf16_f32 v90, v99, v93
	v_cvt_pk_bf16_f32 v91, v94, v91
	v_pk_mul_f32 v[86:87], v[86:87], v[98:99] op_sel_hi:[1,0]
	v_pk_mul_f32 v[84:85], v[84:85], v[98:99] op_sel_hi:[1,0]
	v_max_f32_e32 v80, 0, v80
	v_max_f32_e32 v81, 0, v81
	v_max_f32_e32 v82, 0, v82
	global_store_dwordx4 v[96:97], v[88:91], off nt
	v_max_f32_e32 v84, 0, v84
	v_max_f32_e32 v83, 0, v83
	v_mul_f32_e32 v88, v80, v80
	v_max_f32_e32 v80, 0, v85
	v_mul_f32_e32 v85, v81, v81
	v_max_f32_e32 v81, 0, v86
	v_mul_f32_e32 v86, v82, v82
	v_max_f32_e32 v82, 0, v87
	v_mul_f32_e32 v84, v84, v84
	v_mul_f32_e32 v80, v80, v80
	v_mul_f32_e32 v81, v81, v81
	v_mul_f32_e32 v82, v82, v82
	v_mul_f32_e32 v83, v83, v83
	v_cvt_pk_bf16_f32 v80, v84, v80
	v_cvt_pk_bf16_f32 v81, v81, v82
	v_cvt_pk_bf16_f32 v82, v88, v85
	v_cvt_pk_bf16_f32 v83, v86, v83
	global_store_dwordx4 v[96:97], v[80:83], off offset:256 nt
	v_mov_b32_e32 v84, 0
	s_nop 0
	v_or_b32_e32 v80, 48, v148
	v_ashrrev_i32_e32 v81, 31, v80
	v_lshlrev_b64 v[82:83], 7, v[80:81]
	v_lshl_add_u64 v[82:83], s[52:53], 0, v[82:83]
	v_lshl_add_u64 v[82:83], v[136:137], 4, v[82:83]
	s_and_saveexec_b64 s[42:43], s[6:7]
	s_cbranch_execz .LBB0_2822
	global_load_dwordx4 v[84:87], v[82:83], off
	s_waitcnt vmcnt(0)
	v_mov_b32_e32 v88, v85
	v_mov_b32_e32 v89, v86
	v_mov_b32_e32 v85, v87
	v_pk_add_f32 v[84:85], v[88:89], v[84:85]
	s_nop 0
	v_add_f32_e32 v84, v84, v85
	v_add_f32_e32 v84, 0, v84

.LBB0_2824:
	s_or_b64 exec, exec, s[42:43]
	ds_bpermute_b32 v82, v153, v84
	v_lshlrev_b64 v[80:81], 14, v[80:81]
	v_lshl_add_u64 v[80:81], s[50:51], 0, v[80:81]
	v_lshl_add_u64 v[80:81], v[146:147], 1, v[80:81]
	s_waitcnt lgkmcnt(0)
	v_add_f32_e32 v82, v84, v82
	ds_bpermute_b32 v83, v154, v82
	s_waitcnt lgkmcnt(0)
	v_add_f32_e32 v82, v82, v83
	v_fmamk_f32 v82, v82, 0x3a000000, v158
	v_rsq_f32_e32 v82, v82
	s_nop 0
	v_pk_mul_f32 v[76:77], v[76:77], v[82:83] op_sel_hi:[1,0]
	v_pk_mul_f32 v[74:75], v[74:75], v[82:83] op_sel_hi:[1,0]
	v_pk_mul_f32 v[72:73], v[72:73], v[82:83] op_sel_hi:[1,0]
	v_pk_mul_f32 v[78:79], v[78:79], v[82:83] op_sel_hi:[1,0]
	v_max_f32_e32 v72, 0, v72
	v_max_f32_e32 v77, 0, v77
	v_max_f32_e32 v73, 0, v73
	v_max_f32_e32 v74, 0, v74
	v_max_f32_e32 v76, 0, v76
	v_mul_f32_e32 v83, v72, v72
	v_mul_f32_e32 v72, v77, v77
	v_mul_f32_e32 v77, v73, v73
	v_max_f32_e32 v73, 0, v78
	v_mul_f32_e32 v78, v74, v74
	v_max_f32_e32 v74, 0, v79
	v_max_f32_e32 v75, 0, v75
	v_mul_f32_e32 v76, v76, v76
	v_mul_f32_e32 v73, v73, v73
	v_mul_f32_e32 v74, v74, v74
	v_mul_f32_e32 v75, v75, v75
	v_pk_mul_f32 v[66:67], v[66:67], v[82:83] op_sel_hi:[1,0]
	v_pk_mul_f32 v[64:65], v[64:65], v[82:83] op_sel_hi:[1,0]
	v_cvt_pk_bf16_f32 v72, v76, v72
	v_cvt_pk_bf16_f32 v73, v73, v74
	v_cvt_pk_bf16_f32 v74, v83, v77
	v_cvt_pk_bf16_f32 v75, v78, v75
	v_pk_mul_f32 v[70:71], v[70:71], v[82:83] op_sel_hi:[1,0]
	v_pk_mul_f32 v[68:69], v[68:69], v[82:83] op_sel_hi:[1,0]
	v_max_f32_e32 v64, 0, v64
	v_max_f32_e32 v65, 0, v65
	v_max_f32_e32 v66, 0, v66
	global_store_dwordx4 v[80:81], v[72:75], off nt
	v_max_f32_e32 v68, 0, v68
	v_max_f32_e32 v67, 0, v67
	v_mul_f32_e32 v72, v64, v64
	v_max_f32_e32 v64, 0, v69
	v_mul_f32_e32 v69, v65, v65
	v_max_f32_e32 v65, 0, v70
	v_mul_f32_e32 v70, v66, v66
	v_max_f32_e32 v66, 0, v71
	v_mul_f32_e32 v68, v68, v68
	v_mul_f32_e32 v64, v64, v64
	v_mul_f32_e32 v65, v65, v65
	v_mul_f32_e32 v66, v66, v66
	v_mul_f32_e32 v67, v67, v67
	v_cvt_pk_bf16_f32 v64, v68, v64
	v_cvt_pk_bf16_f32 v65, v65, v66
	v_cvt_pk_bf16_f32 v66, v72, v69
	v_cvt_pk_bf16_f32 v67, v70, v67
	global_store_dwordx4 v[80:81], v[64:67], off offset:256 nt
	v_mov_b32_e32 v68, 0
	s_nop 0
	v_add_u32_e32 v64, 0x80, v148
	v_ashrrev_i32_e32 v65, 31, v64
	v_lshlrev_b64 v[66:67], 7, v[64:65]
	v_lshl_add_u64 v[66:67], s[52:53], 0, v[66:67]
	v_lshl_add_u64 v[66:67], v[136:137], 4, v[66:67]
	s_and_saveexec_b64 s[42:43], s[6:7]
	s_cbranch_execz .LBB0_2826
	global_load_dwordx4 v[68:71], v[66:67], off
	s_waitcnt vmcnt(0)
	v_mov_b32_e32 v72, v69
	v_mov_b32_e32 v73, v70
	v_mov_b32_e32 v69, v71
	v_pk_add_f32 v[68:69], v[72:73], v[68:69]
	s_nop 0
	v_add_f32_e32 v68, v68, v69
	v_add_f32_e32 v68, 0, v68

.LBB0_2828:
	s_or_b64 exec, exec, s[42:43]
	ds_bpermute_b32 v66, v153, v68
	v_lshlrev_b64 v[64:65], 14, v[64:65]
	v_lshl_add_u64 v[64:65], s[50:51], 0, v[64:65]
	v_lshl_add_u64 v[64:65], v[146:147], 1, v[64:65]
	s_waitcnt lgkmcnt(0)
	v_add_f32_e32 v66, v68, v66
	ds_bpermute_b32 v67, v154, v66
	s_waitcnt lgkmcnt(0)
	v_add_f32_e32 v66, v66, v67
	v_fmamk_f32 v66, v66, 0x3a000000, v158
	v_rsq_f32_e32 v66, v66
	s_nop 0
	v_pk_mul_f32 v[60:61], v[60:61], v[66:67] op_sel_hi:[1,0]
	v_pk_mul_f32 v[58:59], v[58:59], v[66:67] op_sel_hi:[1,0]
	v_pk_mul_f32 v[56:57], v[56:57], v[66:67] op_sel_hi:[1,0]
	v_pk_mul_f32 v[62:63], v[62:63], v[66:67] op_sel_hi:[1,0]
	v_max_f32_e32 v56, 0, v56
	v_max_f32_e32 v61, 0, v61
	v_max_f32_e32 v57, 0, v57
	v_max_f32_e32 v58, 0, v58
	v_max_f32_e32 v60, 0, v60
	v_mul_f32_e32 v67, v56, v56
	v_mul_f32_e32 v56, v61, v61
	v_mul_f32_e32 v61, v57, v57
	v_max_f32_e32 v57, 0, v62
	v_mul_f32_e32 v62, v58, v58
	v_max_f32_e32 v58, 0, v63
	v_max_f32_e32 v59, 0, v59
	v_mul_f32_e32 v60, v60, v60
	v_mul_f32_e32 v57, v57, v57
	v_mul_f32_e32 v58, v58, v58
	v_mul_f32_e32 v59, v59, v59
	v_pk_mul_f32 v[50:51], v[50:51], v[66:67] op_sel_hi:[1,0]
	v_pk_mul_f32 v[48:49], v[48:49], v[66:67] op_sel_hi:[1,0]
	v_cvt_pk_bf16_f32 v56, v60, v56
	v_cvt_pk_bf16_f32 v57, v57, v58
	v_cvt_pk_bf16_f32 v58, v67, v61
	v_cvt_pk_bf16_f32 v59, v62, v59
	v_pk_mul_f32 v[54:55], v[54:55], v[66:67] op_sel_hi:[1,0]
	v_pk_mul_f32 v[52:53], v[52:53], v[66:67] op_sel_hi:[1,0]
	v_max_f32_e32 v48, 0, v48
	v_max_f32_e32 v49, 0, v49
	v_max_f32_e32 v50, 0, v50
	global_store_dwordx4 v[64:65], v[56:59], off nt
	v_max_f32_e32 v52, 0, v52
	v_max_f32_e32 v51, 0, v51
	v_mul_f32_e32 v56, v48, v48
	v_max_f32_e32 v48, 0, v53
	v_mul_f32_e32 v53, v49, v49
	v_max_f32_e32 v49, 0, v54
	v_mul_f32_e32 v54, v50, v50
	v_max_f32_e32 v50, 0, v55
	v_mul_f32_e32 v52, v52, v52
	v_mul_f32_e32 v48, v48, v48
	v_mul_f32_e32 v49, v49, v49
	v_mul_f32_e32 v50, v50, v50
	v_mul_f32_e32 v51, v51, v51
	v_cvt_pk_bf16_f32 v48, v52, v48
	v_cvt_pk_bf16_f32 v49, v49, v50
	v_cvt_pk_bf16_f32 v50, v56, v53
	v_cvt_pk_bf16_f32 v51, v54, v51
	global_store_dwordx4 v[64:65], v[48:51], off offset:256 nt
	v_mov_b32_e32 v52, 0
	s_nop 0
	v_add_u32_e32 v48, 0x90, v148
	v_ashrrev_i32_e32 v49, 31, v48
	v_lshlrev_b64 v[50:51], 7, v[48:49]
	v_lshl_add_u64 v[50:51], s[52:53], 0, v[50:51]
	v_lshl_add_u64 v[50:51], v[136:137], 4, v[50:51]
	s_and_saveexec_b64 s[42:43], s[6:7]
	s_cbranch_execz .LBB0_2830
	global_load_dwordx4 v[52:55], v[50:51], off
	s_waitcnt vmcnt(0)
	v_mov_b32_e32 v56, v53
	v_mov_b32_e32 v57, v54
	v_mov_b32_e32 v53, v55
	v_pk_add_f32 v[52:53], v[56:57], v[52:53]
	s_nop 0
	v_add_f32_e32 v52, v52, v53
	v_add_f32_e32 v52, 0, v52

.LBB0_2832:
	s_or_b64 exec, exec, s[42:43]
	ds_bpermute_b32 v50, v153, v52
	v_lshlrev_b64 v[48:49], 14, v[48:49]
	v_lshl_add_u64 v[48:49], s[50:51], 0, v[48:49]
	v_lshl_add_u64 v[48:49], v[146:147], 1, v[48:49]
	s_waitcnt lgkmcnt(0)
	v_add_f32_e32 v50, v52, v50
	ds_bpermute_b32 v51, v154, v50
	s_waitcnt lgkmcnt(0)
	v_add_f32_e32 v50, v50, v51
	v_fmamk_f32 v50, v50, 0x3a000000, v158
	v_rsq_f32_e32 v50, v50
	s_nop 0
	v_pk_mul_f32 v[44:45], v[44:45], v[50:51] op_sel_hi:[1,0]
	v_pk_mul_f32 v[42:43], v[42:43], v[50:51] op_sel_hi:[1,0]
	v_pk_mul_f32 v[40:41], v[40:41], v[50:51] op_sel_hi:[1,0]
	v_pk_mul_f32 v[46:47], v[46:47], v[50:51] op_sel_hi:[1,0]
	v_max_f32_e32 v40, 0, v40
	v_max_f32_e32 v45, 0, v45
	v_max_f32_e32 v41, 0, v41
	v_max_f32_e32 v42, 0, v42
	v_max_f32_e32 v44, 0, v44
	v_mul_f32_e32 v51, v40, v40
	v_mul_f32_e32 v40, v45, v45
	v_mul_f32_e32 v45, v41, v41
	v_max_f32_e32 v41, 0, v46
	v_mul_f32_e32 v46, v42, v42
	v_max_f32_e32 v42, 0, v47
	v_max_f32_e32 v43, 0, v43
	v_mul_f32_e32 v44, v44, v44
	v_mul_f32_e32 v41, v41, v41
	v_mul_f32_e32 v42, v42, v42
	v_mul_f32_e32 v43, v43, v43
	v_pk_mul_f32 v[34:35], v[34:35], v[50:51] op_sel_hi:[1,0]
	v_pk_mul_f32 v[32:33], v[32:33], v[50:51] op_sel_hi:[1,0]
	v_cvt_pk_bf16_f32 v40, v44, v40
	v_cvt_pk_bf16_f32 v41, v41, v42
	v_cvt_pk_bf16_f32 v42, v51, v45
	v_cvt_pk_bf16_f32 v43, v46, v43
	v_pk_mul_f32 v[38:39], v[38:39], v[50:51] op_sel_hi:[1,0]
	v_pk_mul_f32 v[36:37], v[36:37], v[50:51] op_sel_hi:[1,0]
	v_max_f32_e32 v32, 0, v32
	v_max_f32_e32 v33, 0, v33
	v_max_f32_e32 v34, 0, v34
	global_store_dwordx4 v[48:49], v[40:43], off nt
	v_max_f32_e32 v36, 0, v36
	v_max_f32_e32 v35, 0, v35
	v_mul_f32_e32 v40, v32, v32
	v_max_f32_e32 v32, 0, v37
	v_mul_f32_e32 v37, v33, v33
	v_max_f32_e32 v33, 0, v38
	v_mul_f32_e32 v38, v34, v34
	v_max_f32_e32 v34, 0, v39
	v_mul_f32_e32 v36, v36, v36
	v_mul_f32_e32 v32, v32, v32
	v_mul_f32_e32 v33, v33, v33
	v_mul_f32_e32 v34, v34, v34
	v_mul_f32_e32 v35, v35, v35
	v_cvt_pk_bf16_f32 v32, v36, v32
	v_cvt_pk_bf16_f32 v33, v33, v34
	v_cvt_pk_bf16_f32 v34, v40, v37
	v_cvt_pk_bf16_f32 v35, v38, v35
	global_store_dwordx4 v[48:49], v[32:35], off offset:256 nt
	v_mov_b32_e32 v36, 0
	s_nop 0
	v_add_u32_e32 v32, 0xa0, v148
	v_ashrrev_i32_e32 v33, 31, v32
	v_lshlrev_b64 v[34:35], 7, v[32:33]
	v_lshl_add_u64 v[34:35], s[52:53], 0, v[34:35]
	v_lshl_add_u64 v[34:35], v[136:137], 4, v[34:35]
	s_and_saveexec_b64 s[42:43], s[6:7]
	s_cbranch_execz .LBB0_2834
	global_load_dwordx4 v[36:39], v[34:35], off
	s_waitcnt vmcnt(0)
	v_mov_b32_e32 v40, v37
	v_mov_b32_e32 v41, v38
	v_mov_b32_e32 v37, v39
	v_pk_add_f32 v[36:37], v[40:41], v[36:37]
	s_nop 0
	v_add_f32_e32 v36, v36, v37
	v_add_f32_e32 v36, 0, v36

.LBB0_2836:
	s_or_b64 exec, exec, s[42:43]
	ds_bpermute_b32 v34, v153, v36
	v_lshlrev_b64 v[32:33], 14, v[32:33]
	v_lshl_add_u64 v[32:33], s[50:51], 0, v[32:33]
	v_lshl_add_u64 v[32:33], v[146:147], 1, v[32:33]
	s_waitcnt lgkmcnt(0)
	v_add_f32_e32 v34, v36, v34
	ds_bpermute_b32 v35, v154, v34
	s_waitcnt lgkmcnt(0)
	v_add_f32_e32 v34, v34, v35
	v_fmamk_f32 v34, v34, 0x3a000000, v158
	v_rsq_f32_e32 v34, v34
	s_nop 0
	v_pk_mul_f32 v[28:29], v[28:29], v[34:35] op_sel_hi:[1,0]
	v_pk_mul_f32 v[26:27], v[26:27], v[34:35] op_sel_hi:[1,0]
	v_pk_mul_f32 v[24:25], v[24:25], v[34:35] op_sel_hi:[1,0]
	v_pk_mul_f32 v[30:31], v[30:31], v[34:35] op_sel_hi:[1,0]
	v_max_f32_e32 v24, 0, v24
	v_max_f32_e32 v29, 0, v29
	v_max_f32_e32 v25, 0, v25
	v_max_f32_e32 v26, 0, v26
	v_max_f32_e32 v28, 0, v28
	v_mul_f32_e32 v35, v24, v24
	v_mul_f32_e32 v24, v29, v29
	v_mul_f32_e32 v29, v25, v25
	v_max_f32_e32 v25, 0, v30
	v_mul_f32_e32 v30, v26, v26
	v_max_f32_e32 v26, 0, v31
	v_max_f32_e32 v27, 0, v27
	v_mul_f32_e32 v28, v28, v28
	v_mul_f32_e32 v25, v25, v25
	v_mul_f32_e32 v26, v26, v26
	v_mul_f32_e32 v27, v27, v27
	v_pk_mul_f32 v[18:19], v[18:19], v[34:35] op_sel_hi:[1,0]
	v_pk_mul_f32 v[16:17], v[16:17], v[34:35] op_sel_hi:[1,0]
	v_cvt_pk_bf16_f32 v24, v28, v24
	v_cvt_pk_bf16_f32 v25, v25, v26
	v_cvt_pk_bf16_f32 v26, v35, v29
	v_cvt_pk_bf16_f32 v27, v30, v27
	v_pk_mul_f32 v[22:23], v[22:23], v[34:35] op_sel_hi:[1,0]
	v_pk_mul_f32 v[20:21], v[20:21], v[34:35] op_sel_hi:[1,0]
	v_max_f32_e32 v16, 0, v16
	v_max_f32_e32 v17, 0, v17
	v_max_f32_e32 v18, 0, v18
	global_store_dwordx4 v[32:33], v[24:27], off nt
	v_max_f32_e32 v20, 0, v20
	v_max_f32_e32 v19, 0, v19
	v_mul_f32_e32 v24, v16, v16
	v_max_f32_e32 v16, 0, v21
	v_mul_f32_e32 v21, v17, v17
	v_max_f32_e32 v17, 0, v22
	v_mul_f32_e32 v22, v18, v18
	v_max_f32_e32 v18, 0, v23
	v_mul_f32_e32 v20, v20, v20
	v_mul_f32_e32 v16, v16, v16
	v_mul_f32_e32 v17, v17, v17
	v_mul_f32_e32 v18, v18, v18
	v_mul_f32_e32 v19, v19, v19
	v_cvt_pk_bf16_f32 v16, v20, v16
	v_cvt_pk_bf16_f32 v17, v17, v18
	v_cvt_pk_bf16_f32 v18, v24, v21
	v_cvt_pk_bf16_f32 v19, v22, v19
	global_store_dwordx4 v[32:33], v[16:19], off offset:256 nt
	v_mov_b32_e32 v20, 0
	s_nop 0
	v_add_u32_e32 v16, 0xb0, v148
	v_ashrrev_i32_e32 v17, 31, v16
	v_lshlrev_b64 v[18:19], 7, v[16:17]
	v_lshl_add_u64 v[18:19], s[52:53], 0, v[18:19]
	v_lshl_add_u64 v[18:19], v[136:137], 4, v[18:19]
	s_and_saveexec_b64 s[42:43], s[6:7]
	s_cbranch_execz .LBB0_2838
	global_load_dwordx4 v[20:23], v[18:19], off
	s_waitcnt vmcnt(0)
	v_mov_b32_e32 v24, v21
	v_mov_b32_e32 v25, v22
	v_mov_b32_e32 v21, v23
	v_pk_add_f32 v[20:21], v[24:25], v[20:21]
	s_nop 0
	v_add_f32_e32 v20, v20, v21
	v_add_f32_e32 v20, 0, v20

.LBB0_2840:
	s_or_b64 exec, exec, s[42:43]
	ds_bpermute_b32 v18, v153, v20
	v_lshlrev_b64 v[16:17], 14, v[16:17]
	v_lshl_add_u64 v[16:17], s[50:51], 0, v[16:17]
	v_lshl_add_u64 v[16:17], v[146:147], 1, v[16:17]
	s_andn2_b64 vcc, exec, s[14:15]
	s_waitcnt lgkmcnt(0)
	v_add_f32_e32 v18, v20, v18
	ds_bpermute_b32 v19, v154, v18
	s_mov_b64 s[14:15], -1
	s_waitcnt lgkmcnt(0)
	v_add_f32_e32 v18, v18, v19
	v_fmamk_f32 v18, v18, 0x3a000000, v158
	v_rsq_f32_e32 v18, v18
	s_nop 0
	v_pk_mul_f32 v[12:13], v[12:13], v[18:19] op_sel_hi:[1,0]
	v_pk_mul_f32 v[10:11], v[10:11], v[18:19] op_sel_hi:[1,0]
	v_pk_mul_f32 v[8:9], v[8:9], v[18:19] op_sel_hi:[1,0]
	v_pk_mul_f32 v[14:15], v[14:15], v[18:19] op_sel_hi:[1,0]
	v_max_f32_e32 v8, 0, v8
	v_max_f32_e32 v13, 0, v13
	v_max_f32_e32 v9, 0, v9
	v_max_f32_e32 v10, 0, v10
	v_max_f32_e32 v12, 0, v12
	v_mul_f32_e32 v19, v8, v8
	v_mul_f32_e32 v8, v13, v13
	v_mul_f32_e32 v13, v9, v9
	v_max_f32_e32 v9, 0, v14
	v_mul_f32_e32 v14, v10, v10
	v_max_f32_e32 v10, 0, v15
	v_max_f32_e32 v11, 0, v11
	v_mul_f32_e32 v12, v12, v12
	v_mul_f32_e32 v9, v9, v9
	v_mul_f32_e32 v10, v10, v10
	v_mul_f32_e32 v11, v11, v11
	v_pk_mul_f32 v[2:3], v[2:3], v[18:19] op_sel_hi:[1,0]
	v_pk_mul_f32 v[0:1], v[0:1], v[18:19] op_sel_hi:[1,0]
	v_cvt_pk_bf16_f32 v8, v12, v8
	v_cvt_pk_bf16_f32 v9, v9, v10
	v_cvt_pk_bf16_f32 v10, v19, v13
	v_cvt_pk_bf16_f32 v11, v14, v11
	v_pk_mul_f32 v[6:7], v[6:7], v[18:19] op_sel_hi:[1,0]
	v_pk_mul_f32 v[4:5], v[4:5], v[18:19] op_sel_hi:[1,0]
	v_max_f32_e32 v0, 0, v0
	v_max_f32_e32 v1, 0, v1
	v_max_f32_e32 v2, 0, v2
	global_store_dwordx4 v[16:17], v[8:11], off nt
	v_max_f32_e32 v4, 0, v4
	v_max_f32_e32 v3, 0, v3
	v_mul_f32_e32 v8, v0, v0
	v_max_f32_e32 v0, 0, v5
	v_mul_f32_e32 v5, v1, v1
	v_max_f32_e32 v1, 0, v6
	v_mul_f32_e32 v6, v2, v2
	v_max_f32_e32 v2, 0, v7
	v_mul_f32_e32 v4, v4, v4
	v_mul_f32_e32 v0, v0, v0
	v_mul_f32_e32 v1, v1, v1
	v_mul_f32_e32 v2, v2, v2
	v_mul_f32_e32 v3, v3, v3
	v_cvt_pk_bf16_f32 v0, v4, v0
	v_cvt_pk_bf16_f32 v1, v1, v2
	v_cvt_pk_bf16_f32 v2, v8, v5
	v_cvt_pk_bf16_f32 v3, v6, v3
	global_store_dwordx4 v[16:17], v[0:3], off offset:256 nt
	s_cbranch_vccnz .LBB0_2797
	s_and_b64 vcc, exec, s[10:11]
	s_cbranch_vccnz .LBB0_2796
	s_barrier
	s_branch .LBB0_2796
